# scan: per-lane address constants kept in registers for the whole chain (per-chunk setup is 19 adds), compute waves skip the y flush (helper waves flush both halves)
# baseline (speedup 1.0000x reference)
.LBB0_670:
	s_cmpk_lt_u32 s62, 0x100
	s_cbranch_scc1 .LBB0_672
	s_cmp_eq_u32 s65, 0
	s_cbranch_scc1 .LBB0_672
	s_and_b32 s22, s64, 0x800
	v_lshl_add_u32 v21, s22, 2, v68
	v_cndmask_b32_e64 v76, v71, v70, s[4:5]
	ds_read_b128 v[72:75], v21
	v_ashrrev_i32_e32 v77, 31, v76
	v_lshl_add_u64 v[76:77], v[76:77], 0, s[40:41]
	v_lshlrev_b64 v[76:77], 12, v[76:77]
	v_lshl_add_u64 v[76:77], v[54:55], 0, v[76:77]
	s_waitcnt lgkmcnt(0)
	global_store_dwordx4 v[76:77], v[72:75], off

.Lmy_f_main:
	s_cmpk_ge_u32 s62, 0x100
	s_cbranch_scc1 .Lmy_f_hlp
	s_cmp_lg_u32 s65, 0
	s_cbranch_scc1 .Lmy_ck_nz
	v_mov_b32_e32 v208, 0
	v_mov_b32_e32 v209, 0
	v_mov_b32_e32 v210, 0
	v_mov_b32_e32 v211, 0
	v_mov_b32_e32 v212, 0
	v_mov_b32_e32 v213, 0
	v_mov_b32_e32 v214, 0
	v_mov_b32_e32 v215, 0
	v_mov_b32_e32 v216, 0
	v_mov_b32_e32 v217, 0
	v_mov_b32_e32 v218, 0
	v_mov_b32_e32 v219, 0
	v_mov_b32_e32 v220, 0
	v_mov_b32_e32 v221, 0
	v_mov_b32_e32 v222, 0
	v_mov_b32_e32 v223, 0
	v_lshlrev_b32_e32 v0, 4, v224
	v_xor_b32_e32 v1, v224, v234
	v_lshlrev_b32_e32 v1, 4, v1
	v_lshlrev_b32_e32 v2, 4, v234
	v_add_u32_e32 v2, 0x2000, v2
	v_mov_b32_e32 v72, 0x2600
	v_mov_b32_e32 v73, 0x2500
	v_mov_b32_e32 v74, 0x2510
	v_mov_b32_e32 v75, 0x2590
	v_cmp_eq_u32_e64 s[96:97], 0, v234
	v_and_b32_e32 v76, 1, v234
	v_lshrrev_b32_e32 v77, 1, v234
	v_cndmask_b32_e64 v3, v72, v73, s[96:97]
	v_cmp_eq_u32_e64 s[96:97], 1, v234
	v_and_b32_e32 v78, 1, v234
	v_add_u32_e32 v79, 2, v77
	v_cndmask_b32_e64 v4, v72, v74, s[96:97]
	v_cndmask_b32_e64 v5, v72, v75, s[96:97]
	v_lshlrev_b32_e32 v76, 10, v76
	v_lshl_add_u32 v76, v233, 2, v76
	v_add_u32_e32 v8, s62, v76
	v_lshlrev_b32_e32 v76, 9, v234
	v_lshl_add_u32 v76, v233, 2, v76
	v_add_u32_e32 v9, s62, v76
	v_lshl_add_u32 v6, v79, 4, v233
	v_xor_b32_e32 v6, v6, v79
	v_lshlrev_b32_e32 v6, 4, v6
	v_lshl_add_u32 v6, v78, 3, v6
	v_add_u32_e32 v6, 0x2100, v6
	v_lshl_add_u32 v7, v78, 4, v233
	v_xor_b32_e32 v7, v7, v78
	v_lshlrev_b32_e32 v7, 4, v7
	v_lshl_add_u32 v7, v77, 3, v7
	v_add_u32_e32 v7, 0x2100, v7
	v_add_u32_e32 v232, 48, v224
	v_and_b32_e32 v232, 63, v232
	v_lshlrev_b32_e32 v232, 2, v232
.Lmy_ck_nz:
	s_mov_b32 s100, 0xe000
	s_cmp_eq_u32 s23, 0
	s_cselect_b32 s100, 0x1c000, s100
	s_mov_b32 s101, 0x12e00
	s_cselect_b32 s101, 0x22100, s101
	s_lshl_b32 s96, s23, 13
	s_add_i32 s97, s96, 0x18000
	s_add_i32 s96, s96, 0xa000
	v_add_u32_e32 v225, s100, v1
	v_add_u32_e32 v236, s100, v0
	v_add_u32_e32 v226, s100, v2
	v_add_u32_e32 v227, s100, v3
	v_add_u32_e32 v228, s100, v4
	v_add_u32_e32 v229, s100, v5
	v_add_u32_e32 v237, s100, v6
	v_add_u32_e32 v238, s100, v7
	v_add_u32_e32 v230, s96, v8
	v_add_u32_e32 v239, s96, v9
	v_add_u32_e32 v231, s97, v8
	v_add_u32_e32 v26, s101, v1
	v_add_u32_e32 v27, s101, v0
	v_add_u32_e32 v28, s101, v2
	v_add_u32_e32 v29, s101, v3
	v_add_u32_e32 v30, s101, v4
	v_add_u32_e32 v31, s101, v5
	v_add_u32_e32 v32, s101, v6
	v_add_u32_e32 v33, s101, v7
	ds_read_b64 v[80:81], v237
	ds_read_b64 v[82:83], v238
	ds_read_b32 v84, v230
	ds_read_b32 v85, v230 offset:256
	ds_read_b32 v86, v230 offset:512
	ds_read_b32 v87, v230 offset:768
	ds_read_b32 v36, v239
	ds_read_b32 v37, v239 offset:256
	ds_read_b128 v[88:91], v225
	ds_read_b128 v[92:95], v225 offset:1024
	ds_read_b128 v[96:99], v225 offset:2048
	ds_read_b128 v[100:103], v225 offset:3072
	ds_read_b32 v104, v227 offset:4
	ds_read_b32 v105, v227 offset:76
	ds_read_b64 v[106:107], v227 offset:8
	ds_read_b64 v[108:109], v227 offset:40
	ds_read_b32 v126, v229 offset:4
	ds_read_b32 v127, v229 offset:76
	ds_read_b64 v[128:129], v229 offset:8
	ds_read_b64 v[130:131], v229 offset:40
	ds_read_b64 v[110:111], v228
	ds_read_b64 v[112:113], v228 offset:32
	ds_read_b64 v[114:115], v228 offset:64
	ds_read_b64 v[116:117], v228 offset:96
	ds_read_b64 v[118:119], v228 offset:8
	ds_read_b64 v[120:121], v228 offset:40
	ds_read_b64 v[122:123], v228 offset:72
	ds_read_b64 v[124:125], v228 offset:104
	s_waitcnt lgkmcnt(15)
	v_mfma_f32_16x16x4_f32 v[240:243], v80, v36, 0
	v_mfma_f32_16x16x4_f32 v[240:243], v81, v37, v[240:243]
	v_mfma_f32_16x16x4_f32 v[240:243], v88, v208, v[240:243]
	ds_read_b128 v[184:187], v236 offset:4096
	ds_read_b128 v[188:191], v236 offset:5120
	v_mfma_f32_16x16x4_f32 v[244:247], v89, v209, 0
	ds_read_b128 v[192:195], v236 offset:6144
	ds_read_b128 v[196:199], v236 offset:7168
	v_mfma_f32_16x16x4_f32 v[240:243], v90, v210, v[240:243]
	ds_read_b64 v[132:133], v237 offset:9984
	ds_read_b64 v[134:135], v238 offset:9984
	v_mfma_f32_16x16x4_f32 v[244:247], v91, v211, v[244:247]
	ds_read_b32 v136, v230 offset:2048
	ds_read_b32 v137, v230 offset:2304
	v_mfma_f32_16x16x4_f32 v[240:243], v92, v212, v[240:243]
	ds_read_b32 v138, v230 offset:2560
	ds_read_b32 v139, v230 offset:2816
	v_mfma_f32_16x16x4_f32 v[244:247], v93, v213, v[244:247]
	ds_read_b32 v38, v239 offset:2048
	ds_read_b32 v39, v239 offset:2304
	v_mfma_f32_16x16x4_f32 v[240:243], v94, v214, v[240:243]
	ds_read_b128 v[140:143], v225 offset:9984
	ds_read_b128 v[144:147], v225 offset:11008
	v_mfma_f32_16x16x4_f32 v[244:247], v95, v215, v[244:247]
	ds_read_b128 v[148:151], v225 offset:12032
	ds_read_b128 v[152:155], v225 offset:13056
	v_mfma_f32_16x16x4_f32 v[240:243], v96, v216, v[240:243]
	ds_read_b32 v156, v227 offset:9988
	ds_read_b32 v157, v227 offset:10060
	v_mfma_f32_16x16x4_f32 v[244:247], v97, v217, v[244:247]
	ds_read_b64 v[158:159], v227 offset:9992
	ds_read_b64 v[160:161], v227 offset:10024
	v_mfma_f32_16x16x4_f32 v[240:243], v98, v218, v[240:243]
	ds_read_b32 v178, v229 offset:9988
	ds_read_b32 v179, v229 offset:10060
	v_mfma_f32_16x16x4_f32 v[244:247], v99, v219, v[244:247]
	ds_read_b64 v[180:181], v229 offset:9992
	ds_read_b64 v[182:183], v229 offset:10024
	v_mfma_f32_16x16x4_f32 v[240:243], v100, v220, v[240:243]
	ds_read_b64 v[162:163], v228 offset:9984
	ds_read_b64 v[164:165], v228 offset:10016
	v_mfma_f32_16x16x4_f32 v[244:247], v101, v221, v[244:247]
	ds_read_b64 v[166:167], v228 offset:10048
	ds_read_b64 v[168:169], v228 offset:10080
	v_mfma_f32_16x16x4_f32 v[240:243], v102, v222, v[240:243]
	ds_read_b64 v[170:171], v228 offset:9992
	ds_read_b64 v[172:173], v228 offset:10024
	v_mfma_f32_16x16x4_f32 v[244:247], v103, v223, v[244:247]
	ds_read_b64 v[174:175], v228 offset:10056
	ds_read_b64 v[176:177], v228 offset:10088
	s_nop 7
	v_pk_add_f32 v[240:241], v[240:241], v[244:245]
	v_pk_add_f32 v[242:243], v[242:243], v[246:247]
	v_fmac_f32_e32 v241, v104, v240
	s_waitcnt lgkmcnt(13)
	v_pk_fma_f32 v[242:243], v[106:107], v[240:241], v[242:243] op_sel:[0,0,0] op_sel_hi:[1,0,1]
	v_pk_fma_f32 v[242:243], v[108:109], v[240:241], v[242:243] op_sel:[0,1,0] op_sel_hi:[1,1,1]
	v_fmac_f32_e32 v243, v105, v242
	ds_bpermute_b32 v204, v232, v240
	ds_bpermute_b32 v205, v232, v241
	ds_bpermute_b32 v206, v232, v242
	ds_bpermute_b32 v207, v232, v243
	ds_read_b128 v[88:91], v226
	ds_read_b128 v[92:95], v226 offset:64
	ds_read_b128 v[96:99], v226 offset:128
	ds_read_b128 v[100:103], v226 offset:192
	v_mfma_f32_16x16x4_f32 v[72:75], v132, v38, 0
	v_mfma_f32_16x16x4_f32 v[72:75], v133, v39, v[72:75]
	s_waitcnt lgkmcnt(6)
	v_pk_fma_f32 v[240:241], v[110:111], v[204:205], v[240:241] op_sel:[0,0,0] op_sel_hi:[1,0,1]
	v_pk_fma_f32 v[240:241], v[112:113], v[204:205], v[240:241] op_sel:[0,1,0] op_sel_hi:[1,1,1]
	s_waitcnt lgkmcnt(4)
	v_pk_fma_f32 v[240:241], v[114:115], v[206:207], v[240:241] op_sel:[0,0,0] op_sel_hi:[1,0,1]
	v_pk_fma_f32 v[240:241], v[116:117], v[206:207], v[240:241] op_sel:[0,1,0] op_sel_hi:[1,1,1]
	v_pk_fma_f32 v[242:243], v[118:119], v[204:205], v[242:243] op_sel:[0,0,0] op_sel_hi:[1,0,1]
	v_pk_fma_f32 v[242:243], v[120:121], v[204:205], v[242:243] op_sel:[0,1,0] op_sel_hi:[1,1,1]
	v_pk_fma_f32 v[242:243], v[122:123], v[206:207], v[242:243] op_sel:[0,0,0] op_sel_hi:[1,0,1]
	v_pk_fma_f32 v[242:243], v[124:125], v[206:207], v[242:243] op_sel:[0,1,0] op_sel_hi:[1,1,1]
	v_fmac_f32_e32 v241, v126, v240
	v_pk_fma_f32 v[242:243], v[128:129], v[240:241], v[242:243] op_sel:[0,0,0] op_sel_hi:[1,0,1]
	v_pk_fma_f32 v[242:243], v[130:131], v[240:241], v[242:243] op_sel:[0,1,0] op_sel_hi:[1,1,1]
	v_fmac_f32_e32 v243, v127, v242
	v_cndmask_b32_e64 v200, v240, v84, s[98:99]
	v_cndmask_b32_e64 v201, v241, v85, s[98:99]
	v_cndmask_b32_e64 v202, v242, v86, s[98:99]
	v_cndmask_b32_e64 v203, v243, v87, s[98:99]
	v_mov_b32_e32 v252, v240
	v_mov_b32_e32 v253, v241
	v_mov_b32_e32 v254, v242
	v_mov_b32_e32 v255, v243
	v_mfma_f32_16x16x4_f32 v[208:211], v184, v200, v[208:211]
	v_mfma_f32_16x16x4_f32 v[212:215], v188, v200, v[212:215]
	v_mfma_f32_16x16x4_f32 v[216:219], v192, v200, v[216:219]
	v_mfma_f32_16x16x4_f32 v[220:223], v196, v200, v[220:223]
	v_permlane32_swap_b32_e32 v252, v254
	v_permlane32_swap_b32_e32 v253, v255
	v_mfma_f32_16x16x4_f32 v[208:211], v185, v201, v[208:211]
	v_mfma_f32_16x16x4_f32 v[212:215], v189, v201, v[212:215]
	v_mfma_f32_16x16x4_f32 v[216:219], v193, v201, v[216:219]
	v_mfma_f32_16x16x4_f32 v[220:223], v197, v201, v[220:223]
	v_mfma_f32_16x16x4_f32 v[208:211], v186, v202, v[208:211]
	v_mfma_f32_16x16x4_f32 v[212:215], v190, v202, v[212:215]
	v_mfma_f32_16x16x4_f32 v[216:219], v194, v202, v[216:219]
	v_mfma_f32_16x16x4_f32 v[220:223], v198, v202, v[220:223]
	v_mfma_f32_16x16x4_f32 v[208:211], v187, v203, v[208:211]
	v_mfma_f32_16x16x4_f32 v[212:215], v191, v203, v[212:215]
	v_mfma_f32_16x16x4_f32 v[216:219], v195, v203, v[216:219]
	v_mfma_f32_16x16x4_f32 v[220:223], v199, v203, v[220:223]
	v_mfma_f32_16x16x4_f32 v[248:251], v82, v252, v[240:243]
	v_mfma_f32_16x16x4_f32 v[248:251], v83, v253, v[248:251]
	s_waitcnt lgkmcnt(0)
	s_nop 4
	v_pk_mul_f32 v[208:209], v[208:209], v[88:89]
	v_pk_mul_f32 v[210:211], v[210:211], v[90:91]
	s_nop 0
	v_mfma_f32_16x16x4_f32 v[72:75], v140, v208, v[72:75]
	v_pk_mul_f32 v[212:213], v[212:213], v[92:93]
	v_mfma_f32_16x16x4_f32 v[244:247], v141, v209, 0
	v_pk_mul_f32 v[214:215], v[214:215], v[94:95]
	v_mfma_f32_16x16x4_f32 v[72:75], v142, v210, v[72:75]
	v_pk_mul_f32 v[216:217], v[216:217], v[96:97]
	v_mfma_f32_16x16x4_f32 v[244:247], v143, v211, v[244:247]
	v_pk_mul_f32 v[218:219], v[218:219], v[98:99]
	v_mfma_f32_16x16x4_f32 v[72:75], v144, v212, v[72:75]
	v_pk_mul_f32 v[220:221], v[220:221], v[100:101]
	v_mfma_f32_16x16x4_f32 v[244:247], v145, v213, v[244:247]
	v_pk_mul_f32 v[222:223], v[222:223], v[102:103]
	v_mfma_f32_16x16x4_f32 v[72:75], v146, v214, v[72:75]
	s_mov_b64 exec, s[98:99]
	ds_write_b32 v231, v248
	ds_write_b32 v231, v249 offset:256
	ds_write_b32 v231, v250 offset:512
	ds_write_b32 v231, v251 offset:768
	s_mov_b64 exec, -1
	ds_read_b128 v[184:187], v236 offset:14080
	ds_read_b128 v[188:191], v236 offset:15104
	v_mfma_f32_16x16x4_f32 v[244:247], v147, v215, v[244:247]
	ds_read_b128 v[192:195], v236 offset:16128
	ds_read_b128 v[196:199], v236 offset:17152
	v_mfma_f32_16x16x4_f32 v[72:75], v148, v216, v[72:75]
	ds_read_b64 v[80:81], v32
	ds_read_b64 v[82:83], v33
	ds_read_b32 v84, v230 offset:4096
	ds_read_b32 v85, v230 offset:4352
	v_mfma_f32_16x16x4_f32 v[244:247], v149, v217, v[244:247]
	ds_read_b32 v86, v230 offset:4608
	ds_read_b32 v87, v230 offset:4864
	ds_read_b32 v36, v239 offset:4096
	ds_read_b32 v37, v239 offset:4352
	v_mfma_f32_16x16x4_f32 v[72:75], v150, v218, v[72:75]
	ds_read_b128 v[88:91], v26
	ds_read_b128 v[92:95], v26 offset:1024
	ds_read_b128 v[96:99], v26 offset:2048
	ds_read_b128 v[100:103], v26 offset:3072
	v_mfma_f32_16x16x4_f32 v[244:247], v151, v219, v[244:247]
	ds_read_b32 v104, v29 offset:4
	ds_read_b32 v105, v29 offset:76
	ds_read_b64 v[106:107], v29 offset:8
	ds_read_b64 v[108:109], v29 offset:40
	v_mfma_f32_16x16x4_f32 v[72:75], v152, v220, v[72:75]
	ds_read_b32 v126, v31 offset:4
	ds_read_b32 v127, v31 offset:76
	ds_read_b64 v[128:129], v31 offset:8
	ds_read_b64 v[130:131], v31 offset:40
	v_mfma_f32_16x16x4_f32 v[244:247], v153, v221, v[244:247]
	ds_read_b64 v[110:111], v30
	ds_read_b64 v[112:113], v30 offset:32
	ds_read_b64 v[114:115], v30 offset:64
	ds_read_b64 v[116:117], v30 offset:96
	v_mfma_f32_16x16x4_f32 v[72:75], v154, v222, v[72:75]
	ds_read_b64 v[118:119], v30 offset:8
	ds_read_b64 v[120:121], v30 offset:40
	ds_read_b64 v[122:123], v30 offset:72
	ds_read_b64 v[124:125], v30 offset:104
	v_mfma_f32_16x16x4_f32 v[244:247], v155, v223, v[244:247]
	s_nop 9
	v_pk_add_f32 v[72:73], v[72:73], v[244:245]
	v_pk_add_f32 v[74:75], v[74:75], v[246:247]
	v_fmac_f32_e32 v73, v156, v72
	v_pk_fma_f32 v[74:75], v[158:159], v[72:73], v[74:75] op_sel:[0,0,0] op_sel_hi:[1,0,1]
	v_pk_fma_f32 v[74:75], v[160:161], v[72:73], v[74:75] op_sel:[0,1,0] op_sel_hi:[1,1,1]
	v_fmac_f32_e32 v75, v157, v74
	ds_bpermute_b32 v204, v232, v72
	ds_bpermute_b32 v205, v232, v73
	ds_bpermute_b32 v206, v232, v74
	ds_bpermute_b32 v207, v232, v75
	ds_read_b128 v[140:143], v226 offset:9984
	ds_read_b128 v[144:147], v226 offset:10048
	ds_read_b128 v[148:151], v226 offset:10112
	ds_read_b128 v[152:155], v226 offset:10176
	s_waitcnt lgkmcnt(14)
	v_mfma_f32_16x16x4_f32 v[240:243], v80, v36, 0
	v_mfma_f32_16x16x4_f32 v[240:243], v81, v37, v[240:243]
	s_waitcnt lgkmcnt(6)
	v_pk_fma_f32 v[72:73], v[162:163], v[204:205], v[72:73] op_sel:[0,0,0] op_sel_hi:[1,0,1]
	v_pk_fma_f32 v[72:73], v[164:165], v[204:205], v[72:73] op_sel:[0,1,0] op_sel_hi:[1,1,1]
	s_waitcnt lgkmcnt(4)
	v_pk_fma_f32 v[72:73], v[166:167], v[206:207], v[72:73] op_sel:[0,0,0] op_sel_hi:[1,0,1]
	v_pk_fma_f32 v[72:73], v[168:169], v[206:207], v[72:73] op_sel:[0,1,0] op_sel_hi:[1,1,1]
	v_pk_fma_f32 v[74:75], v[170:171], v[204:205], v[74:75] op_sel:[0,0,0] op_sel_hi:[1,0,1]
	v_pk_fma_f32 v[74:75], v[172:173], v[204:205], v[74:75] op_sel:[0,1,0] op_sel_hi:[1,1,1]
	v_pk_fma_f32 v[74:75], v[174:175], v[206:207], v[74:75] op_sel:[0,0,0] op_sel_hi:[1,0,1]
	v_pk_fma_f32 v[74:75], v[176:177], v[206:207], v[74:75] op_sel:[0,1,0] op_sel_hi:[1,1,1]
	v_fmac_f32_e32 v73, v178, v72
	v_pk_fma_f32 v[74:75], v[180:181], v[72:73], v[74:75] op_sel:[0,0,0] op_sel_hi:[1,0,1]
	v_pk_fma_f32 v[74:75], v[182:183], v[72:73], v[74:75] op_sel:[0,1,0] op_sel_hi:[1,1,1]
	v_fmac_f32_e32 v75, v179, v74
	v_cndmask_b32_e64 v200, v72, v136, s[98:99]
	v_cndmask_b32_e64 v201, v73, v137, s[98:99]
	v_cndmask_b32_e64 v202, v74, v138, s[98:99]
	v_cndmask_b32_e64 v203, v75, v139, s[98:99]
	v_mov_b32_e32 v252, v72
	v_mov_b32_e32 v253, v73
	v_mov_b32_e32 v254, v74
	v_mov_b32_e32 v255, v75
	v_mfma_f32_16x16x4_f32 v[208:211], v184, v200, v[208:211]
	v_mfma_f32_16x16x4_f32 v[212:215], v188, v200, v[212:215]
	v_mfma_f32_16x16x4_f32 v[216:219], v192, v200, v[216:219]
	v_mfma_f32_16x16x4_f32 v[220:223], v196, v200, v[220:223]
	v_permlane32_swap_b32_e32 v252, v254
	v_permlane32_swap_b32_e32 v253, v255
	v_mfma_f32_16x16x4_f32 v[208:211], v185, v201, v[208:211]
	v_mfma_f32_16x16x4_f32 v[212:215], v189, v201, v[212:215]
	v_mfma_f32_16x16x4_f32 v[216:219], v193, v201, v[216:219]
	v_mfma_f32_16x16x4_f32 v[220:223], v197, v201, v[220:223]
	v_mfma_f32_16x16x4_f32 v[208:211], v186, v202, v[208:211]
	v_mfma_f32_16x16x4_f32 v[212:215], v190, v202, v[212:215]
	v_mfma_f32_16x16x4_f32 v[216:219], v194, v202, v[216:219]
	v_mfma_f32_16x16x4_f32 v[220:223], v198, v202, v[220:223]
	v_mfma_f32_16x16x4_f32 v[208:211], v187, v203, v[208:211]
	v_mfma_f32_16x16x4_f32 v[212:215], v191, v203, v[212:215]
	v_mfma_f32_16x16x4_f32 v[216:219], v195, v203, v[216:219]
	v_mfma_f32_16x16x4_f32 v[220:223], v199, v203, v[220:223]
	v_mfma_f32_16x16x4_f32 v[248:251], v134, v252, v[72:75]
	v_mfma_f32_16x16x4_f32 v[248:251], v135, v253, v[248:251]
	s_waitcnt lgkmcnt(0)
	s_nop 4
	v_pk_mul_f32 v[208:209], v[208:209], v[140:141]
	v_pk_mul_f32 v[210:211], v[210:211], v[142:143]
	s_nop 0
	v_mfma_f32_16x16x4_f32 v[240:243], v88, v208, v[240:243]
	v_pk_mul_f32 v[212:213], v[212:213], v[144:145]
	v_mfma_f32_16x16x4_f32 v[244:247], v89, v209, 0
	v_pk_mul_f32 v[214:215], v[214:215], v[146:147]
	v_mfma_f32_16x16x4_f32 v[240:243], v90, v210, v[240:243]
	v_pk_mul_f32 v[216:217], v[216:217], v[148:149]
	v_mfma_f32_16x16x4_f32 v[244:247], v91, v211, v[244:247]
	v_pk_mul_f32 v[218:219], v[218:219], v[150:151]
	v_mfma_f32_16x16x4_f32 v[240:243], v92, v212, v[240:243]
	v_pk_mul_f32 v[220:221], v[220:221], v[152:153]
	v_mfma_f32_16x16x4_f32 v[244:247], v93, v213, v[244:247]
	v_pk_mul_f32 v[222:223], v[222:223], v[154:155]
	v_mfma_f32_16x16x4_f32 v[240:243], v94, v214, v[240:243]
	s_mov_b64 exec, s[98:99]
	ds_write_b32 v231, v248 offset:2048
	ds_write_b32 v231, v249 offset:2304
	ds_write_b32 v231, v250 offset:2560
	ds_write_b32 v231, v251 offset:2816
	s_mov_b64 exec, -1
	ds_read_b128 v[184:187], v27 offset:4096
	ds_read_b128 v[188:191], v27 offset:5120
	v_mfma_f32_16x16x4_f32 v[244:247], v95, v215, v[244:247]
	ds_read_b128 v[192:195], v27 offset:6144
	ds_read_b128 v[196:199], v27 offset:7168
	v_mfma_f32_16x16x4_f32 v[240:243], v96, v216, v[240:243]
	ds_read_b64 v[132:133], v32 offset:9984
	ds_read_b64 v[134:135], v33 offset:9984
	ds_read_b32 v136, v230 offset:6144
	ds_read_b32 v137, v230 offset:6400
	v_mfma_f32_16x16x4_f32 v[244:247], v97, v217, v[244:247]
	ds_read_b32 v138, v230 offset:6656
	ds_read_b32 v139, v230 offset:6912
	ds_read_b32 v38, v239 offset:6144
	ds_read_b32 v39, v239 offset:6400
	v_mfma_f32_16x16x4_f32 v[240:243], v98, v218, v[240:243]
	ds_read_b128 v[140:143], v26 offset:9984
	ds_read_b128 v[144:147], v26 offset:11008
	ds_read_b128 v[148:151], v26 offset:12032
	ds_read_b128 v[152:155], v26 offset:13056
	v_mfma_f32_16x16x4_f32 v[244:247], v99, v219, v[244:247]
	ds_read_b32 v156, v29 offset:9988
	ds_read_b32 v157, v29 offset:10060
	ds_read_b64 v[158:159], v29 offset:9992
	ds_read_b64 v[160:161], v29 offset:10024
	v_mfma_f32_16x16x4_f32 v[240:243], v100, v220, v[240:243]
	ds_read_b32 v178, v31 offset:9988
	ds_read_b32 v179, v31 offset:10060
	ds_read_b64 v[180:181], v31 offset:9992
	ds_read_b64 v[182:183], v31 offset:10024
	v_mfma_f32_16x16x4_f32 v[244:247], v101, v221, v[244:247]
	ds_read_b64 v[162:163], v30 offset:9984
	ds_read_b64 v[164:165], v30 offset:10016
	ds_read_b64 v[166:167], v30 offset:10048
	ds_read_b64 v[168:169], v30 offset:10080
	v_mfma_f32_16x16x4_f32 v[240:243], v102, v222, v[240:243]
	ds_read_b64 v[170:171], v30 offset:9992
	ds_read_b64 v[172:173], v30 offset:10024
	ds_read_b64 v[174:175], v30 offset:10056
	ds_read_b64 v[176:177], v30 offset:10088
	v_mfma_f32_16x16x4_f32 v[244:247], v103, v223, v[244:247]
	s_nop 9
	v_pk_add_f32 v[240:241], v[240:241], v[244:245]
	v_pk_add_f32 v[242:243], v[242:243], v[246:247]
	v_fmac_f32_e32 v241, v104, v240
	v_pk_fma_f32 v[242:243], v[106:107], v[240:241], v[242:243] op_sel:[0,0,0] op_sel_hi:[1,0,1]
	v_pk_fma_f32 v[242:243], v[108:109], v[240:241], v[242:243] op_sel:[0,1,0] op_sel_hi:[1,1,1]
	v_fmac_f32_e32 v243, v105, v242
	ds_bpermute_b32 v204, v232, v240
	ds_bpermute_b32 v205, v232, v241
	ds_bpermute_b32 v206, v232, v242
	ds_bpermute_b32 v207, v232, v243
	ds_read_b128 v[88:91], v28
	ds_read_b128 v[92:95], v28 offset:64
	ds_read_b128 v[96:99], v28 offset:128
	ds_read_b128 v[100:103], v28 offset:192
	s_waitcnt lgkmcnt(14)
	v_mfma_f32_16x16x4_f32 v[72:75], v132, v38, 0
	v_mfma_f32_16x16x4_f32 v[72:75], v133, v39, v[72:75]
	s_waitcnt lgkmcnt(6)
	v_pk_fma_f32 v[240:241], v[110:111], v[204:205], v[240:241] op_sel:[0,0,0] op_sel_hi:[1,0,1]
	v_pk_fma_f32 v[240:241], v[112:113], v[204:205], v[240:241] op_sel:[0,1,0] op_sel_hi:[1,1,1]
	s_waitcnt lgkmcnt(4)
	v_pk_fma_f32 v[240:241], v[114:115], v[206:207], v[240:241] op_sel:[0,0,0] op_sel_hi:[1,0,1]
	v_pk_fma_f32 v[240:241], v[116:117], v[206:207], v[240:241] op_sel:[0,1,0] op_sel_hi:[1,1,1]
	v_pk_fma_f32 v[242:243], v[118:119], v[204:205], v[242:243] op_sel:[0,0,0] op_sel_hi:[1,0,1]
	v_pk_fma_f32 v[242:243], v[120:121], v[204:205], v[242:243] op_sel:[0,1,0] op_sel_hi:[1,1,1]
	v_pk_fma_f32 v[242:243], v[122:123], v[206:207], v[242:243] op_sel:[0,0,0] op_sel_hi:[1,0,1]
	v_pk_fma_f32 v[242:243], v[124:125], v[206:207], v[242:243] op_sel:[0,1,0] op_sel_hi:[1,1,1]
	v_fmac_f32_e32 v241, v126, v240
	v_pk_fma_f32 v[242:243], v[128:129], v[240:241], v[242:243] op_sel:[0,0,0] op_sel_hi:[1,0,1]
	v_pk_fma_f32 v[242:243], v[130:131], v[240:241], v[242:243] op_sel:[0,1,0] op_sel_hi:[1,1,1]
	v_fmac_f32_e32 v243, v127, v242
	v_cndmask_b32_e64 v200, v240, v84, s[98:99]
	v_cndmask_b32_e64 v201, v241, v85, s[98:99]
	v_cndmask_b32_e64 v202, v242, v86, s[98:99]
	v_cndmask_b32_e64 v203, v243, v87, s[98:99]
	v_mov_b32_e32 v252, v240
	v_mov_b32_e32 v253, v241
	v_mov_b32_e32 v254, v242
	v_mov_b32_e32 v255, v243
	v_mfma_f32_16x16x4_f32 v[208:211], v184, v200, v[208:211]
	v_mfma_f32_16x16x4_f32 v[212:215], v188, v200, v[212:215]
	v_mfma_f32_16x16x4_f32 v[216:219], v192, v200, v[216:219]
	v_mfma_f32_16x16x4_f32 v[220:223], v196, v200, v[220:223]
	v_permlane32_swap_b32_e32 v252, v254
	v_permlane32_swap_b32_e32 v253, v255
	v_mfma_f32_16x16x4_f32 v[208:211], v185, v201, v[208:211]
	v_mfma_f32_16x16x4_f32 v[212:215], v189, v201, v[212:215]
	v_mfma_f32_16x16x4_f32 v[216:219], v193, v201, v[216:219]
	v_mfma_f32_16x16x4_f32 v[220:223], v197, v201, v[220:223]
	v_mfma_f32_16x16x4_f32 v[208:211], v186, v202, v[208:211]
	v_mfma_f32_16x16x4_f32 v[212:215], v190, v202, v[212:215]
	v_mfma_f32_16x16x4_f32 v[216:219], v194, v202, v[216:219]
	v_mfma_f32_16x16x4_f32 v[220:223], v198, v202, v[220:223]
	v_mfma_f32_16x16x4_f32 v[208:211], v187, v203, v[208:211]
	v_mfma_f32_16x16x4_f32 v[212:215], v191, v203, v[212:215]
	v_mfma_f32_16x16x4_f32 v[216:219], v195, v203, v[216:219]
	v_mfma_f32_16x16x4_f32 v[220:223], v199, v203, v[220:223]
	v_mfma_f32_16x16x4_f32 v[248:251], v82, v252, v[240:243]
	v_mfma_f32_16x16x4_f32 v[248:251], v83, v253, v[248:251]
	s_waitcnt lgkmcnt(0)
	s_nop 4
	v_pk_mul_f32 v[208:209], v[208:209], v[88:89]
	v_pk_mul_f32 v[210:211], v[210:211], v[90:91]
	s_nop 0
	v_mfma_f32_16x16x4_f32 v[72:75], v140, v208, v[72:75]
	v_pk_mul_f32 v[212:213], v[212:213], v[92:93]
	v_mfma_f32_16x16x4_f32 v[244:247], v141, v209, 0
	v_pk_mul_f32 v[214:215], v[214:215], v[94:95]
	v_mfma_f32_16x16x4_f32 v[72:75], v142, v210, v[72:75]
	v_pk_mul_f32 v[216:217], v[216:217], v[96:97]
	v_mfma_f32_16x16x4_f32 v[244:247], v143, v211, v[244:247]
	v_pk_mul_f32 v[218:219], v[218:219], v[98:99]
	v_mfma_f32_16x16x4_f32 v[72:75], v144, v212, v[72:75]
	v_pk_mul_f32 v[220:221], v[220:221], v[100:101]
	v_mfma_f32_16x16x4_f32 v[244:247], v145, v213, v[244:247]
	v_pk_mul_f32 v[222:223], v[222:223], v[102:103]
	v_mfma_f32_16x16x4_f32 v[72:75], v146, v214, v[72:75]
	s_mov_b64 exec, s[98:99]
	ds_write_b32 v231, v248 offset:4096
	ds_write_b32 v231, v249 offset:4352
	ds_write_b32 v231, v250 offset:4608
	ds_write_b32 v231, v251 offset:4864
	s_mov_b64 exec, -1
	ds_read_b128 v[184:187], v27 offset:14080
	ds_read_b128 v[188:191], v27 offset:15104
	v_mfma_f32_16x16x4_f32 v[244:247], v147, v215, v[244:247]
	ds_read_b128 v[192:195], v27 offset:16128
	ds_read_b128 v[196:199], v27 offset:17152
	v_mfma_f32_16x16x4_f32 v[72:75], v148, v216, v[72:75]
	v_mfma_f32_16x16x4_f32 v[244:247], v149, v217, v[244:247]
	v_mfma_f32_16x16x4_f32 v[72:75], v150, v218, v[72:75]
	v_mfma_f32_16x16x4_f32 v[244:247], v151, v219, v[244:247]
	v_mfma_f32_16x16x4_f32 v[72:75], v152, v220, v[72:75]
	v_mfma_f32_16x16x4_f32 v[244:247], v153, v221, v[244:247]
	v_mfma_f32_16x16x4_f32 v[72:75], v154, v222, v[72:75]
	v_mfma_f32_16x16x4_f32 v[244:247], v155, v223, v[244:247]
	s_nop 9
	v_pk_add_f32 v[72:73], v[72:73], v[244:245]
	v_pk_add_f32 v[74:75], v[74:75], v[246:247]
	v_fmac_f32_e32 v73, v156, v72
	v_pk_fma_f32 v[74:75], v[158:159], v[72:73], v[74:75] op_sel:[0,0,0] op_sel_hi:[1,0,1]
	v_pk_fma_f32 v[74:75], v[160:161], v[72:73], v[74:75] op_sel:[0,1,0] op_sel_hi:[1,1,1]
	v_fmac_f32_e32 v75, v157, v74
	ds_bpermute_b32 v204, v232, v72
	ds_bpermute_b32 v205, v232, v73
	ds_bpermute_b32 v206, v232, v74
	ds_bpermute_b32 v207, v232, v75
	ds_read_b128 v[140:143], v28 offset:9984
	ds_read_b128 v[144:147], v28 offset:10048
	ds_read_b128 v[148:151], v28 offset:10112
	ds_read_b128 v[152:155], v28 offset:10176
	s_waitcnt lgkmcnt(6)
	v_pk_fma_f32 v[72:73], v[162:163], v[204:205], v[72:73] op_sel:[0,0,0] op_sel_hi:[1,0,1]
	v_pk_fma_f32 v[72:73], v[164:165], v[204:205], v[72:73] op_sel:[0,1,0] op_sel_hi:[1,1,1]
	s_waitcnt lgkmcnt(4)
	v_pk_fma_f32 v[72:73], v[166:167], v[206:207], v[72:73] op_sel:[0,0,0] op_sel_hi:[1,0,1]
	v_pk_fma_f32 v[72:73], v[168:169], v[206:207], v[72:73] op_sel:[0,1,0] op_sel_hi:[1,1,1]
	v_pk_fma_f32 v[74:75], v[170:171], v[204:205], v[74:75] op_sel:[0,0,0] op_sel_hi:[1,0,1]
	v_pk_fma_f32 v[74:75], v[172:173], v[204:205], v[74:75] op_sel:[0,1,0] op_sel_hi:[1,1,1]
	v_pk_fma_f32 v[74:75], v[174:175], v[206:207], v[74:75] op_sel:[0,0,0] op_sel_hi:[1,0,1]
	v_pk_fma_f32 v[74:75], v[176:177], v[206:207], v[74:75] op_sel:[0,1,0] op_sel_hi:[1,1,1]
	v_fmac_f32_e32 v73, v178, v72
	v_pk_fma_f32 v[74:75], v[180:181], v[72:73], v[74:75] op_sel:[0,0,0] op_sel_hi:[1,0,1]
	v_pk_fma_f32 v[74:75], v[182:183], v[72:73], v[74:75] op_sel:[0,1,0] op_sel_hi:[1,1,1]
	v_fmac_f32_e32 v75, v179, v74
	v_cndmask_b32_e64 v200, v72, v136, s[98:99]
	v_cndmask_b32_e64 v201, v73, v137, s[98:99]
	v_cndmask_b32_e64 v202, v74, v138, s[98:99]
	v_cndmask_b32_e64 v203, v75, v139, s[98:99]
	v_mov_b32_e32 v252, v72
	v_mov_b32_e32 v253, v73
	v_mov_b32_e32 v254, v74
	v_mov_b32_e32 v255, v75
	v_mfma_f32_16x16x4_f32 v[208:211], v184, v200, v[208:211]
	v_mfma_f32_16x16x4_f32 v[212:215], v188, v200, v[212:215]
	v_mfma_f32_16x16x4_f32 v[216:219], v192, v200, v[216:219]
	v_mfma_f32_16x16x4_f32 v[220:223], v196, v200, v[220:223]
	v_permlane32_swap_b32_e32 v252, v254
	v_permlane32_swap_b32_e32 v253, v255
	v_mfma_f32_16x16x4_f32 v[208:211], v185, v201, v[208:211]
	v_mfma_f32_16x16x4_f32 v[212:215], v189, v201, v[212:215]
	v_mfma_f32_16x16x4_f32 v[216:219], v193, v201, v[216:219]
	v_mfma_f32_16x16x4_f32 v[220:223], v197, v201, v[220:223]
	v_mfma_f32_16x16x4_f32 v[208:211], v186, v202, v[208:211]
	v_mfma_f32_16x16x4_f32 v[212:215], v190, v202, v[212:215]
	v_mfma_f32_16x16x4_f32 v[216:219], v194, v202, v[216:219]
	v_mfma_f32_16x16x4_f32 v[220:223], v198, v202, v[220:223]
	v_mfma_f32_16x16x4_f32 v[208:211], v187, v203, v[208:211]
	v_mfma_f32_16x16x4_f32 v[212:215], v191, v203, v[212:215]
	v_mfma_f32_16x16x4_f32 v[216:219], v195, v203, v[216:219]
	v_mfma_f32_16x16x4_f32 v[220:223], v199, v203, v[220:223]
	v_mfma_f32_16x16x4_f32 v[248:251], v134, v252, v[72:75]
	v_mfma_f32_16x16x4_f32 v[248:251], v135, v253, v[248:251]
	s_waitcnt lgkmcnt(0)
	s_nop 4
	v_pk_mul_f32 v[208:209], v[208:209], v[140:141]
	v_pk_mul_f32 v[210:211], v[210:211], v[142:143]
	v_pk_mul_f32 v[212:213], v[212:213], v[144:145]
	v_pk_mul_f32 v[214:215], v[214:215], v[146:147]
	v_pk_mul_f32 v[216:217], v[216:217], v[148:149]
	v_pk_mul_f32 v[218:219], v[218:219], v[150:151]
	v_pk_mul_f32 v[220:221], v[220:221], v[152:153]
	v_pk_mul_f32 v[222:223], v[222:223], v[154:155]
	s_mov_b64 exec, s[98:99]
	ds_write_b32 v231, v248 offset:6144
	ds_write_b32 v231, v249 offset:6400
	ds_write_b32 v231, v250 offset:6656
	ds_write_b32 v231, v251 offset:6912
	s_mov_b64 exec, -1
	s_branch .LBB0_655
.Lmy_f_hlp:
	s_cmp_eq_u32 s65, 0
	s_cbranch_scc1 .Lmy_f_nofl
	v_subrev_u32_e32 v70, 16, v70
	v_add_u32_e32 v71, 16, v71
	s_and_b32 s96, s64, 0x800
	v_lshl_add_u32 v21, s96, 2, v68
	v_add_u32_e32 v21, 0xfffff000, v21
	v_cndmask_b32_e64 v76, v71, v70, s[4:5]
	ds_read_b128 v[72:75], v21
	v_ashrrev_i32_e32 v77, 31, v76
	v_lshl_add_u64 v[76:77], v[76:77], 0, s[40:41]
	v_lshlrev_b64 v[76:77], 12, v[76:77]
	v_lshl_add_u64 v[76:77], v[54:55], 0, v[76:77]
	s_waitcnt lgkmcnt(0)
	global_store_dwordx4 v[76:77], v[72:75], off
	v_add_u32_e32 v70, 16, v70
	v_subrev_u32_e32 v71, 16, v71
